# attention prologue: unit-0 rope-table loads issued before the first vmcnt(0) wait into free VGPRs (one L2 round trip per slot removed)
# speedup vs baseline: 1.0052x; 1.0012x over previous
; __device__ __forceinline__ float bflo(unsigned w) { return __uint_as_float(w << 16); }
; __device__ __forceinline__ float bfhi(unsigned w) { return __uint_as_float(w & 0xffff0000u); }
; __device__ __forceinline__ int v_st(int k, int c) { const int kk = (k & ~0xC) | ((k & 4) << 1) | ((k & 8) >> 1); return ((kk >> 3) * 4 + (c >> 5)) * 512 + ((kk & 7) * 32 + (c & 31)) * 2; }
; __device__ __forceinline__ int v_rd_base(int lane) { return ((lane & 3) << 3) | (((lane >> 2) & 3) << 6) | (((lane >> 4) & 1) << 5) | (((lane >> 5) & 1) << 8); }
; #define SLOAD(i, k0) do { sr_[i].vs0 = LD8(&Vh[(long)((k0) + sr) * LDK + sc]); sr_[i].vs1 = LD8(&Vh[(long)((k0) + 32 + sr) * LDK + sc]); \
;     sr_[i].ks0 = LD8(&Kh[(long)((k0) + sr) * LDK + sc]); sr_[i].ks1 = LD8(&Kh[(long)((k0) + 32 + sr) * LDK + sc]); } while (0)
; __device__ __forceinline__ void attn_body(const bf16_t* __restrict__ Qb, const bf16_t* __restrict__ Kh, const bf16_t* __restrict__ Vh, const bf16_t* __restrict__ Zb, ...
;     ...
;     float l_reg = 0; f32x16 o[4] = {}; bf16x8 qr[8];
;     const bf16_t* Qw = Qb + (long)(wid * QBLK + r32) * LDQ + hi * 8;
; #pragma unroll
;     for (int d0 = 0; d0 < 8; ++d0) qr[d0] = *reinterpret_cast<const bf16x8*>(Qw + d0 * 16);
;     const int sr = tid >> 4, sc = (tid & 15) * 8, vst0 = v_st(sr, sc), vst1 = v_st(32 + sr, sc);
;     const int vb0 = (int)(uintptr_t)V_lds + v_rd_base(lane);
;     struct { bf16x8 vs0, vs1, ks0, ks1; } sr_[2];
;     ...
;     SLOAD(0, 0); SLOAD(1, KVBLK);
;     {
;         float ss = 0.f; int hi_ = hi; const float* qg_ = qg;
;         asm volatile("" : "+v"(hi_)); asm volatile("" : "+s"(qg_));
; #pragma unroll
;         for (int d0 = 0; d0 < 8; ++d0) { const u32x4 w = *reinterpret_cast<const u32x4*>(&qr[d0]);
;             ss += bflo(w.x) * bflo(w.x) + bfhi(w.x) * bfhi(w.x) + bflo(w.y) * bflo(w.y) + bfhi(w.y) * bfhi(w.y) + bflo(w.z) * bflo(w.z) + bfhi(w.z) * bfhi(w.z) + bflo(w.w) * bflo(w.w) + bfhi(w.w) * bfhi(w.w); }
;         ss += __shfl_xor(ss, 32);
;         const float rinv = rsqrtf(ss * (1.f / 128.f) + 1e-6f) * (SCALE * 1.4426950408889634f);
;         const int tpos = tq0 + wid * QBLK + r32; const float* rope_ = rope; asm volatile("" : "+s"(rope_));
;     ...
;                 const f32x4* tp = (const f32x4*)(rope_ + ((ax ? (tpos & 63) : (tpos >> 6)) * 32 + dd * 16 + hi_ * 8) * 2);
;                 const f32x4 t0 = tp[0], t1 = tp[1], t2 = tp[2], t3 = tp[3];
.LBB0_485:
	s_lshl_b32 s23, s7, 8
	s_and_b32 s20, s8, 1
	s_add_i32 s8, s23, s22
	s_mul_i32 s16, s8, 0x1800
	s_mul_hi_u32 s7, s8, 0x1800
	s_add_u32 s16, s78, s16
	s_addc_u32 s17, s79, s7
	s_lshl_b32 s7, s20, 9
	s_lshl_b32 s6, s6, 7
	s_add_i32 s6, s6, s7
	s_mov_b32 s7, s9
	s_lshl_b64 s[18:19], s[6:7], 1
	s_add_u32 s16, s16, s18
	v_mov_b32_e32 v200, v176
	s_addc_u32 s17, s17, s19
	v_mov_b64_e32 v[0:1], s[16:17]
	v_ashrrev_i32_e32 v2, 1, v200
	v_bfe_u32 v199, v200, 5, 1
	v_bfi_b32 v3, s25, v2, v200
	v_mad_i64_i32 v[0:1], s[6:7], v3, s30, v[0:1]
	v_lshlrev_b32_e32 v184, 4, v199
	v_lshl_add_u64 v[0:1], v[0:1], 0, v[184:185]
	global_load_dwordx4 v[74:77], v[0:1], off offset:160
	global_load_dwordx4 v[78:81], v[0:1], off offset:128
	global_load_dwordx4 v[40:43], v[0:1], off
	global_load_dwordx4 v[32:35], v[0:1], off offset:32
	global_load_dwordx4 v[44:47], v[0:1], off offset:64
	global_load_dwordx4 v[36:39], v[0:1], off offset:96
	global_load_dwordx4 v[56:59], v[0:1], off offset:192
	global_load_dwordx4 v[94:97], v[0:1], off offset:224
	v_ashrrev_i32_e32 v186, 4, v200
	v_and_b32_e32 v202, 0xffffffe0, v2
	v_and_b32_e32 v1, 0xfffff0, v186
	v_lshlrev_b32_e32 v2, 1, v186
	v_lshlrev_b32_e32 v0, 3, v200
	v_and_or_b32 v1, v2, 8, v1
	v_lshrrev_b32_e32 v61, 1, v1
	v_bfe_u32 v62, v0, 5, 2
	v_or_b32_e32 v61, v61, v62
	v_lshrrev_b32_e32 v60, 1, v186
	v_lshlrev_b32_e32 v92, 9, v61
	v_and_b32_e32 v61, 3, v186
	v_add_u32_e32 v189, 32, v186
	v_and_or_b32 v60, v60, 4, v61
	v_lshlrev_b32_e32 v93, 6, v60
	v_and_b32_e32 v60, 0xfffff0, v189
	v_lshlrev_b32_e32 v61, 1, v189
	v_and_or_b32 v60, v61, 8, v60
	s_mul_i32 s7, s22, 0x1800
	v_lshrrev_b32_e32 v60, 1, v60
	s_mul_hi_u32 s6, s22, 0x1800
	s_add_u32 s7, s78, s7
	v_or_b32_e32 v60, v60, v62
	s_addc_u32 s6, s79, s6
	s_lshl_b32 s41, s20, 8
	v_lshlrev_b32_e32 v107, 9, v60
	s_add_u32 s20, s7, s41
	v_add_u32_e32 v16, 64, v186
	s_addc_u32 s21, s6, 0
	v_and_b32_e32 v198, 0x78, v0
	v_mad_i64_i32 v[16:17], s[6:7], v16, s31, 0
	v_or_b32_e32 v16, v16, v198
	v_lshl_add_u64 v[20:21], v[16:17], 1, s[20:21]
	v_add_u32_e32 v16, 0x60, v186
	v_mad_i64_i32 v[0:1], s[6:7], v186, s31, 0
	v_mad_i64_i32 v[2:3], s[6:7], v189, s31, 0
	v_mad_i64_i32 v[16:17], s[6:7], v16, s31, 0
	v_or_b32_e32 v0, v0, v198
	v_or_b32_e32 v2, v2, v198
	v_or_b32_e32 v16, v16, v198
	v_lshl_add_u64 v[0:1], v[0:1], 1, s[20:21]
	v_lshl_add_u64 v[2:3], v[2:3], 1, s[20:21]
	v_lshl_add_u64 v[24:25], v[16:17], 1, s[20:21]
	v_mov_b32_e32 v106, v199
	v_readlane_b32 s44, v254, 27
	v_cmp_lt_i32_e32 vcc, v179, v195
	v_and_b32_e32 v201, 31, v200
	global_load_dwordx4 v[8:11], v[0:1], off offset:2560
	global_load_dwordx4 v[4:7], v[0:1], off offset:2048
	global_load_dwordx4 v[12:15], v[2:3], off offset:2560
	s_nop 0
	global_load_dwordx4 v[0:3], v[2:3], off offset:2048
	s_nop 0
	global_load_dwordx4 v[16:19], v[20:21], off offset:2560
	s_nop 0
	global_load_dwordx4 v[20:23], v[20:21], off offset:2048
	s_nop 0
	global_load_dwordx4 v[28:31], v[24:25], off offset:2560
	s_nop 0
	global_load_dwordx4 v[24:27], v[24:25], off offset:2048
	v_readlane_b32 s58, v254, 41
	v_readlane_b32 s59, v254, 42
	v_lshlrev_b32_e32 v48, 3, v106
	s_mov_b64 s[42:43], s[58:59]
	v_ashrrev_i32_e32 v49, 31, v48
	s_mov_b64 s[6:7], s[10:11]
	v_lshl_add_u64 v[68:69], v[48:49], 2, s[42:43]
	flat_load_dwordx4 v[98:101], v[68:69] offset:128
	flat_load_dwordx4 v[102:105], v[68:69] offset:144
	flat_load_dwordx4 v[52:55], v[68:69]
	flat_load_dwordx4 v[48:51], v[68:69] offset:16
	v_lshlrev_b32_e32 v165, 4, v106
	v_or_b32_e32 v219, s23, v201
	v_add_u32_e32 v219, v219, v202
	v_and_b32_e32 v219, 0xffffffc0, v219
	v_add_u32_e32 v166, v165, v219
	v_ashrrev_i32_e32 v167, 31, v166
	v_lshl_add_u64 v[166:167], v[166:167], 2, s[6:7]
	flat_load_dwordx4 v[236:239], v[166:167]
	flat_load_dwordx4 v[240:243], v[166:167] offset:16
	flat_load_dwordx4 v[244:247], v[166:167] offset:32
	flat_load_dwordx4 v[248:251], v[166:167] offset:48
	v_lshlrev_b32_e32 v188, 1, v198
	v_readlane_b32 s45, v254, 28
	v_readlane_b32 s46, v254, 29
	v_readlane_b32 s47, v254, 30
	v_readlane_b32 s48, v254, 31
	v_readlane_b32 s49, v254, 32
	v_readlane_b32 s50, v254, 33
	v_readlane_b32 s51, v254, 34
	v_readlane_b32 s52, v254, 35
	s_waitcnt vmcnt(0)
	v_lshlrev_b32_e32 v125, 16, v43
	v_and_b32_e32 v129, 0xffff0000, v43
	v_lshlrev_b32_e32 v131, 16, v42
	v_and_b32_e32 v63, 0xffff0000, v74
	v_and_b32_e32 v62, 0xffff0000, v78
	v_lshlrev_b32_e32 v61, 16, v74
	v_lshlrev_b32_e32 v60, 16, v78
	v_pk_mul_f32 v[64:65], v[62:63], v[62:63]
	v_and_b32_e32 v85, 0xffff0000, v94
	v_pk_fma_f32 v[66:67], v[60:61], v[60:61], v[64:65]
	v_lshlrev_b32_e32 v65, 16, v75
	v_lshlrev_b32_e32 v64, 16, v79
	v_pk_fma_f32 v[70:71], v[64:65], v[64:65], v[66:67]
	v_and_b32_e32 v67, 0xffff0000, v75
	v_and_b32_e32 v66, 0xffff0000, v79
	v_pk_fma_f32 v[72:73], v[66:67], v[66:67], v[70:71]
	v_lshlrev_b32_e32 v71, 16, v76
	v_lshlrev_b32_e32 v70, 16, v80
	v_pk_fma_f32 v[74:75], v[70:71], v[70:71], v[72:73]
	v_and_b32_e32 v73, 0xffff0000, v76
	v_and_b32_e32 v72, 0xffff0000, v80
	v_pk_fma_f32 v[78:79], v[72:73], v[72:73], v[74:75]
	v_lshlrev_b32_e32 v75, 16, v77
	v_lshlrev_b32_e32 v74, 16, v81
	v_pk_fma_f32 v[78:79], v[74:75], v[74:75], v[78:79]
	v_and_b32_e32 v77, 0xffff0000, v77
	v_and_b32_e32 v76, 0xffff0000, v81
	v_and_b32_e32 v84, 0xffff0000, v56
	v_pk_fma_f32 v[122:123], v[76:77], v[76:77], v[78:79]
	v_lshlrev_b32_e32 v83, 16, v94
	v_lshlrev_b32_e32 v82, 16, v56
	v_pk_mul_f32 v[78:79], v[84:85], v[84:85]
	v_lshlrev_b32_e32 v87, 16, v95
	v_pk_fma_f32 v[78:79], v[82:83], v[82:83], v[78:79]
	v_lshlrev_b32_e32 v86, 16, v57
	v_lshlrev_b32_e32 v90, 16, v58
	v_and_b32_e32 v80, 0xffff0000, v58
; __device__ __forceinline__ float bflo(unsigned w) { return __uint_as_float(w << 16); }
; __device__ __forceinline__ float bfhi(unsigned w) { return __uint_as_float(w & 0xffff0000u); }
; __device__ __forceinline__ void attn_body(const bf16_t* __restrict__ Qb, const bf16_t* __restrict__ Kh, const bf16_t* __restrict__ Vh, const bf16_t* __restrict__ Zb, ...
;     ...
;         for (int d0 = 0; d0 < 8; ++d0) { const u32x4 w = *reinterpret_cast<const u32x4*>(&qr[d0]);
;             ss += bflo(w.x) * bflo(w.x) + bfhi(w.x) * bfhi(w.x) + bflo(w.y) * bflo(w.y) + bfhi(w.y) * bfhi(w.y) + bflo(w.z) * bflo(w.z) + bfhi(w.z) * bfhi(w.z) + bflo(w.w) * bflo(w.w) + bfhi(w.w) * bfhi(w.w); }
;         ss += __shfl_xor(ss, 32);
;         const float rinv = rsqrtf(ss * (1.f / 128.f) + 1e-6f) * (SCALE * 1.4426950408889634f);
;         const int tpos = tq0 + wid * QBLK + r32; const float* rope_ = rope; asm volatile("" : "+s"(rope_));
; #pragma unroll
;         for (int ax = 0; ax < 2; ++ax)
; #pragma unroll
;             for (int dd = 0; dd < 2; ++dd) { const int da = ax * 4 + dd, db = da + 2;
;                 const u32x4 wa = *reinterpret_cast<const u32x4*>(&qr[da]), wb = *reinterpret_cast<const u32x4*>(&qr[db]);
;                 float xa[8] = {bflo(wa.x), bfhi(wa.x), bflo(wa.y), bfhi(wa.y), bflo(wa.z), bfhi(wa.z), bflo(wa.w), bfhi(wa.w)};
;                 float xb[8] = {bflo(wb.x), bfhi(wb.x), bflo(wb.y), bfhi(wb.y), bflo(wb.z), bfhi(wb.z), bflo(wb.w), bfhi(wb.w)};
;                 const float* ga = qg_ + da * 16 + hi_ * 8; const float* gb = qg_ + db * 16 + hi_ * 8;
;                 const f32x4* tp = (const f32x4*)(rope_ + ((ax ? (tpos & 63) : (tpos >> 6)) * 32 + dd * 16 + hi_ * 8) * 2);
;                 const f32x4 t0 = tp[0], t1 = tp[1], t2 = tp[2], t3 = tp[3];
;                 const float csv[8] = {t0[0], t0[2], t1[0], t1[2], t2[0], t2[2], t3[0], t3[2]}, snv[8] = {t0[1], t0[3], t1[1], t1[3], t2[1], t2[3], t3[1], t3[3]};
; #pragma unroll
;                 for (int e = 0; e < 8; ++e) { const float x1 = xa[e] * rinv * ga[e], x2 = xb[e] * rinv * gb[e];
;                     xa[e] = x1 * csv[e] - x2 * snv[e]; xb[e] = x2 * csv[e] + x1 * snv[e]; }
	v_cndmask_b32_e32 v58, v177, v179, vcc
	v_pk_fma_f32 v[78:79], v[86:87], v[86:87], v[78:79]
	v_and_b32_e32 v89, 0xffff0000, v95
	v_and_b32_e32 v88, 0xffff0000, v57
	v_lshlrev_b32_e32 v135, 2, v58
	v_or_b32_e32 v58, s23, v201
	v_pk_fma_f32 v[56:57], v[88:89], v[88:89], v[78:79]
	v_lshlrev_b32_e32 v91, 16, v96
	v_add_u32_e32 v164, v58, v202
	v_pk_fma_f32 v[56:57], v[90:91], v[90:91], v[56:57]
	v_and_b32_e32 v81, 0xffff0000, v96
	v_and_b32_e32 v58, 0xffffffc0, v164
	v_pk_fma_f32 v[56:57], v[80:81], v[80:81], v[56:57]
	v_lshlrev_b32_e32 v79, 16, v97
	v_lshlrev_b32_e32 v78, 16, v59
	v_add_u32_e32 v58, v165, v58
	v_pk_fma_f32 v[94:95], v[78:79], v[78:79], v[56:57]
	v_and_b32_e32 v57, 0xffff0000, v97
	v_and_b32_e32 v56, 0xffff0000, v59
	v_ashrrev_i32_e32 v59, 31, v58
	v_pk_fma_f32 v[96:97], v[56:57], v[56:57], v[94:95]
	v_and_b32_e32 v95, 48, v188
	v_lshl_add_u64 v[58:59], v[58:59], 2, s[6:7]
	v_or3_b32 v94, v107, v93, v95
	v_mov_b64_e32 v[106:107], v[236:237]
	v_mov_b64_e32 v[108:109], v[238:239]
	v_mov_b64_e32 v[110:111], v[240:241]
	v_mov_b64_e32 v[112:113], v[242:243]
	v_mov_b64_e32 v[114:115], v[244:245]
	v_mov_b64_e32 v[116:117], v[246:247]
	v_mov_b64_e32 v[118:119], v[248:249]
	v_mov_b64_e32 v[120:121], v[250:251]
	v_lshlrev_b32_e32 v130, 16, v46
	v_and_b32_e32 v43, 0xffff0000, v42
	v_and_b32_e32 v42, 0xffff0000, v46
	v_lshlrev_b32_e32 v46, 16, v45
	v_and_b32_e32 v136, 0xffff0000, v45
	v_and_b32_e32 v45, 0xffff0000, v40
	v_and_b32_e32 v151, 0xffff0000, v32
	v_lshlrev_b32_e32 v139, 16, v40
	v_lshlrev_b32_e32 v149, 16, v32
	v_mov_b32_e32 v160, v45
	v_mov_b32_e32 v161, v151
	v_lshlrev_b32_e32 v124, 16, v47
	v_and_b32_e32 v128, 0xffff0000, v47
	v_lshlrev_b32_e32 v47, 16, v41
	v_lshlrev_b32_e32 v138, 16, v44
	v_and_b32_e32 v44, 0xffff0000, v44
	v_lshlrev_b32_e32 v145, 16, v33
	v_and_b32_e32 v150, 0xffff0000, v36
	v_mov_b32_e32 v158, v139
	v_mov_b32_e32 v159, v149
	v_pk_mul_f32 v[160:161], v[160:161], v[160:161]
	v_and_b32_e32 v137, 0xffff0000, v41
	v_and_b32_e32 v147, 0xffff0000, v33
	v_lshlrev_b32_e32 v148, 16, v36
	v_mov_b32_e32 v154, v47
	v_mov_b32_e32 v155, v145
	v_pk_fma_f32 v[158:159], v[158:159], v[158:159], v[160:161]
	v_mov_b32_e32 v162, v44
	v_mov_b32_e32 v163, v150
	v_lshlrev_b32_e32 v143, 16, v34
	v_lshlrev_b32_e32 v144, 16, v37
	v_mov_b32_e32 v156, v137
	v_mov_b32_e32 v157, v147
	v_pk_fma_f32 v[154:155], v[154:155], v[154:155], v[158:159]
	v_mov_b32_e32 v160, v138
	v_mov_b32_e32 v161, v148
	v_pk_mul_f32 v[162:163], v[162:163], v[162:163]
	v_lshlrev_b32_e32 v140, 16, v39
	v_and_b32_e32 v40, 0xffff0000, v39
	v_and_b32_e32 v39, 0xffff0000, v34
	v_and_b32_e32 v146, 0xffff0000, v37
	v_mov_b32_e32 v36, v131
	v_mov_b32_e32 v37, v143
	v_pk_fma_f32 v[154:155], v[156:157], v[156:157], v[154:155]
	v_mov_b32_e32 v156, v46
	v_mov_b32_e32 v157, v144
	v_pk_fma_f32 v[160:161], v[160:161], v[160:161], v[162:163]
	v_lshlrev_b32_e32 v141, 16, v35
	v_lshlrev_b32_e32 v142, 16, v38
	v_mov_b32_e32 v152, v43
	v_mov_b32_e32 v153, v39
	v_pk_fma_f32 v[36:37], v[36:37], v[36:37], v[154:155]
	v_mov_b32_e32 v158, v136
	v_mov_b32_e32 v159, v146
	v_pk_fma_f32 v[156:157], v[156:157], v[156:157], v[160:161]
	v_and_b32_e32 v41, 0xffff0000, v35
	v_and_b32_e32 v38, 0xffff0000, v38
	v_mov_b32_e32 v32, v125
	v_mov_b32_e32 v33, v141
	v_pk_fma_f32 v[36:37], v[152:153], v[152:153], v[36:37]
	v_mov_b32_e32 v152, v130
	v_mov_b32_e32 v153, v142
	v_pk_fma_f32 v[156:157], v[158:159], v[158:159], v[156:157]
	v_mov_b32_e32 v34, v129
	v_mov_b32_e32 v35, v41
	v_pk_fma_f32 v[32:33], v[32:33], v[32:33], v[36:37]
	v_mov_b32_e32 v154, v42
	v_mov_b32_e32 v155, v38
	v_pk_fma_f32 v[152:153], v[152:153], v[152:153], v[156:157]
	v_pk_fma_f32 v[32:33], v[34:35], v[34:35], v[32:33]
	v_mov_b32_e32 v34, v124
	v_mov_b32_e32 v35, v140
	v_pk_fma_f32 v[152:153], v[154:155], v[154:155], v[152:153]
	v_mov_b32_e32 v36, v128
	v_mov_b32_e32 v37, v40
	v_pk_fma_f32 v[34:35], v[34:35], v[34:35], v[152:153]
	v_add_f32_e32 v32, v32, v33
	v_pk_fma_f32 v[34:35], v[36:37], v[36:37], v[34:35]
	s_waitcnt lgkmcnt(0)
	v_mov_b32_e32 v134, v100
	v_add_f32_e32 v32, v32, v34
	v_add_f32_e32 v32, v32, v35
	v_add_f32_e32 v32, v32, v122
	v_add_f32_e32 v32, v32, v123
	v_add_f32_e32 v32, v32, v96
	v_add_f32_e32 v32, v32, v97
	ds_bpermute_b32 v33, v135, v32
	v_mov_b32_e32 v34, v98
	v_mov_b32_e32 v35, v52
	v_mov_b32_e32 v52, v99
	v_mov_b32_e32 v135, v54
	s_waitcnt lgkmcnt(0)
	v_add_f32_e32 v32, v32, v33
	v_fmamk_f32 v32, v32, 0x3c000000, v196
	v_mul_f32_e32 v33, 0x4b800000, v32
	v_cmp_gt_f32_e32 vcc, s34, v32
	v_mov_b32_e32 v54, v101
	v_mov_b32_e32 v132, v102
	v_cndmask_b32_e32 v32, v32, v33, vcc
	v_rsq_f32_e32 v32, v32
	v_mov_b32_e32 v133, v48
	v_mov_b32_e32 v48, v103
	v_mov_b32_e32 v126, v104
	v_mul_f32_e32 v33, 0x45800000, v32
	v_cndmask_b32_e32 v32, v32, v33, vcc
	v_mul_f32_e32 v32, 0x3e0293ee, v32
	v_pk_mul_f32 v[36:37], v[32:33], v[138:139] op_sel_hi:[0,1]
	v_pk_mul_f32 v[34:35], v[34:35], v[36:37]
	v_mov_b32_e32 v127, v50
	s_waitcnt vmcnt(0)
; __device__ __forceinline__ unsigned cvt_pk(float lo, float hi) { unsigned r; asm volatile("v_cvt_pk_bf16_f32 %0, %1, %2" : "=v"(r) : "v"(lo), "v"(hi)); return r; }
; __device__ __forceinline__ float bflo(unsigned w) { return __uint_as_float(w << 16); }
; __device__ __forceinline__ float bfhi(unsigned w) { return __uint_as_float(w & 0xffff0000u); }
; __device__ __forceinline__ void attn_body(const bf16_t* __restrict__ Qb, const bf16_t* __restrict__ Kh, const bf16_t* __restrict__ Vh, const bf16_t* __restrict__ Zb, ...
;     ...
;             for (int dd = 0; dd < 2; ++dd) { const int da = ax * 4 + dd, db = da + 2;
;                 const u32x4 wa = *reinterpret_cast<const u32x4*>(&qr[da]), wb = *reinterpret_cast<const u32x4*>(&qr[db]);
;                 float xa[8] = {bflo(wa.x), bfhi(wa.x), bflo(wa.y), bfhi(wa.y), bflo(wa.z), bfhi(wa.z), bflo(wa.w), bfhi(wa.w)};
;                 float xb[8] = {bflo(wb.x), bfhi(wb.x), bflo(wb.y), bfhi(wb.y), bflo(wb.z), bfhi(wb.z), bflo(wb.w), bfhi(wb.w)};
;                 const float* ga = qg_ + da * 16 + hi_ * 8; const float* gb = qg_ + db * 16 + hi_ * 8;
;                 const f32x4* tp = (const f32x4*)(rope_ + ((ax ? (tpos & 63) : (tpos >> 6)) * 32 + dd * 16 + hi_ * 8) * 2);
;                 const f32x4 t0 = tp[0], t1 = tp[1], t2 = tp[2], t3 = tp[3];
;                 const float csv[8] = {t0[0], t0[2], t1[0], t1[2], t2[0], t2[2], t3[0], t3[2]}, snv[8] = {t0[1], t0[3], t1[1], t1[3], t2[1], t2[3], t3[1], t3[3]};
; #pragma unroll
;                 for (int e = 0; e < 8; ++e) { const float x1 = xa[e] * rinv * ga[e], x2 = xb[e] * rinv * gb[e];
;                     xa[e] = x1 * csv[e] - x2 * snv[e]; xb[e] = x2 * csv[e] + x1 * snv[e]; }
;                 u32x4 oa, ob; oa.x = cvt_pk(xa[0], xa[1]); oa.y = cvt_pk(xa[2], xa[3]); oa.z = cvt_pk(xa[4], xa[5]); oa.w = cvt_pk(xa[6], xa[7]);
;                 ob.x = cvt_pk(xb[0], xb[1]); ob.y = cvt_pk(xb[2], xb[3]); ob.z = cvt_pk(xb[4], xb[5]); ob.w = cvt_pk(xb[6], xb[7]);
;                 qr[da] = *reinterpret_cast<bf16x8*>(&oa); qr[db] = *reinterpret_cast<bf16x8*>(&ob);
;                 __builtin_amdgcn_sched_barrier(0); }
	v_pk_mul_f32 v[36:37], v[106:107], v[34:35] op_sel:[0,1] op_sel_hi:[1,0]
	v_pk_mul_f32 v[34:35], v[106:107], v[34:35]
	v_sub_f32_e32 v33, v36, v37
	v_add_f32_e32 v96, v34, v35
	v_pk_mul_f32 v[34:35], v[32:33], v[44:45] op_sel_hi:[0,1]
	v_pk_mul_f32 v[34:35], v[52:53], v[34:35]
	v_mov_b32_e32 v50, v105
	v_pk_mul_f32 v[36:37], v[108:109], v[34:35] op_sel:[0,1] op_sel_hi:[1,0]
	v_pk_mul_f32 v[34:35], v[108:109], v[34:35]
	v_sub_f32_e32 v44, v36, v37
	v_add_f32_e32 v45, v34, v35
	v_pk_mul_f32 v[34:35], v[32:33], v[46:47] op_sel_hi:[0,1]
	v_pk_mul_f32 v[34:35], v[34:35], v[134:135]
	v_readlane_b32 s53, v254, 36
	v_pk_mul_f32 v[36:37], v[110:111], v[34:35] op_sel:[0,1] op_sel_hi:[1,0]
	v_pk_mul_f32 v[34:35], v[110:111], v[34:35]
	v_sub_f32_e32 v46, v36, v37
	v_add_f32_e32 v47, v34, v35
	v_pk_mul_f32 v[34:35], v[32:33], v[136:137] op_sel_hi:[0,1]
	v_pk_mul_f32 v[34:35], v[34:35], v[54:55]
	v_readlane_b32 s54, v254, 37
	v_pk_mul_f32 v[36:37], v[112:113], v[34:35] op_sel:[0,1] op_sel_hi:[1,0]
	v_pk_mul_f32 v[34:35], v[112:113], v[34:35]
	v_sub_f32_e32 v52, v36, v37
	v_add_f32_e32 v53, v35, v34
	v_pk_mul_f32 v[34:35], v[32:33], v[130:131] op_sel_hi:[0,1]
	v_pk_mul_f32 v[34:35], v[34:35], v[132:133]
	v_readlane_b32 s55, v254, 38
	v_pk_mul_f32 v[36:37], v[114:115], v[34:35] op_sel:[0,1] op_sel_hi:[1,0]
	v_pk_mul_f32 v[34:35], v[114:115], v[34:35]
	v_sub_f32_e32 v54, v36, v37
	v_add_f32_e32 v55, v35, v34
	v_pk_mul_f32 v[34:35], v[32:33], v[42:43] op_sel_hi:[0,1]
	v_pk_mul_f32 v[34:35], v[34:35], v[48:49]
	v_readlane_b32 s56, v254, 39
	v_pk_mul_f32 v[36:37], v[116:117], v[34:35] op_sel:[0,1] op_sel_hi:[1,0]
	v_pk_mul_f32 v[34:35], v[116:117], v[34:35]
	v_sub_f32_e32 v42, v36, v37
	v_add_f32_e32 v43, v35, v34
	v_pk_mul_f32 v[34:35], v[32:33], v[124:125] op_sel_hi:[0,1]
	v_pk_mul_f32 v[34:35], v[34:35], v[126:127]
	v_readlane_b32 s57, v254, 40
	v_pk_mul_f32 v[36:37], v[118:119], v[34:35] op_sel:[0,1] op_sel_hi:[1,0]
	v_pk_mul_f32 v[34:35], v[118:119], v[34:35]
	v_sub_f32_e32 v48, v36, v37
	v_add_f32_e32 v49, v35, v34
	v_pk_mul_f32 v[34:35], v[32:33], v[128:129] op_sel_hi:[0,1]
	v_pk_mul_f32 v[34:35], v[34:35], v[50:51]
	v_cvt_pk_bf16_f32 v116, v33, v44
	v_cvt_pk_bf16_f32 v117, v46, v52
	v_cvt_pk_bf16_f32 v118, v54, v42
	s_nop 0
	v_pk_mul_f32 v[36:37], v[120:121], v[34:35] op_sel:[0,1] op_sel_hi:[1,0]
	v_pk_mul_f32 v[34:35], v[120:121], v[34:35]
	v_sub_f32_e32 v36, v36, v37
	v_add_f32_e32 v34, v35, v34
	v_cvt_pk_bf16_f32 v119, v48, v36
	v_cvt_pk_bf16_f32 v112, v96, v45
	v_cvt_pk_bf16_f32 v113, v47, v53
	v_cvt_pk_bf16_f32 v114, v55, v43
	v_cvt_pk_bf16_f32 v115, v49, v34
	flat_load_dwordx4 v[34:37], v[68:69] offset:192
	flat_load_dwordx4 v[42:45], v[68:69] offset:64
	flat_load_dwordx4 v[46:49], v[68:69] offset:208
	flat_load_dwordx4 v[50:53], v[68:69] offset:80
	flat_load_dwordx4 v[96:99], v[58:59] offset:128
	flat_load_dwordx4 v[100:103], v[58:59] offset:144
	flat_load_dwordx4 v[104:107], v[58:59] offset:160
	flat_load_dwordx4 v[108:111], v[58:59] offset:176
	v_pk_mul_f32 v[54:55], v[32:33], v[148:149] op_sel_hi:[0,1]
	v_pk_mul_f32 v[58:59], v[32:33], v[150:151] op_sel_hi:[0,1]
	v_pk_mul_f32 v[120:121], v[32:33], v[144:145] op_sel_hi:[0,1]
	v_pk_mul_f32 v[122:123], v[32:33], v[146:147] op_sel_hi:[0,1]
	v_pk_mul_f32 v[124:125], v[32:33], v[142:143] op_sel_hi:[0,1]
	v_pk_mul_f32 v[38:39], v[32:33], v[38:39] op_sel_hi:[0,1]
	v_pk_mul_f32 v[126:127], v[32:33], v[140:141] op_sel_hi:[0,1]
	v_pk_mul_f32 v[40:41], v[32:33], v[40:41] op_sel_hi:[0,1]
	s_waitcnt vmcnt(0) lgkmcnt(0)
	v_mov_b32_e32 v128, v34
	v_mov_b32_e32 v129, v42
	v_mov_b32_e32 v42, v35
	v_mov_b32_e32 v34, v36
	v_mov_b32_e32 v35, v44
	v_mov_b32_e32 v44, v37
	v_mov_b32_e32 v36, v46
	v_mov_b32_e32 v37, v50
	v_mov_b32_e32 v50, v47
	v_mov_b32_e32 v46, v48
	v_mov_b32_e32 v47, v52
	v_mov_b32_e32 v52, v49
	v_pk_mul_f32 v[48:49], v[54:55], v[128:129]
	v_pk_mul_f32 v[42:43], v[58:59], v[42:43]
	v_pk_mul_f32 v[34:35], v[120:121], v[34:35]
	v_pk_mul_f32 v[44:45], v[122:123], v[44:45]
	v_pk_mul_f32 v[36:37], v[124:125], v[36:37]
	v_pk_mul_f32 v[38:39], v[38:39], v[50:51]
	v_pk_mul_f32 v[46:47], v[126:127], v[46:47]
	v_pk_mul_f32 v[40:41], v[40:41], v[52:53]
	v_pk_mul_f32 v[50:51], v[96:97], v[48:49] op_sel:[0,1] op_sel_hi:[1,0]
	v_pk_mul_f32 v[48:49], v[96:97], v[48:49]
	v_pk_mul_f32 v[52:53], v[98:99], v[42:43] op_sel:[0,1] op_sel_hi:[1,0]
	v_pk_mul_f32 v[42:43], v[98:99], v[42:43]
	v_pk_mul_f32 v[54:55], v[100:101], v[34:35] op_sel:[0,1] op_sel_hi:[1,0]
	v_pk_mul_f32 v[34:35], v[100:101], v[34:35]
	v_pk_mul_f32 v[58:59], v[102:103], v[44:45] op_sel:[0,1] op_sel_hi:[1,0]
	v_pk_mul_f32 v[44:45], v[102:103], v[44:45]
	v_pk_mul_f32 v[96:97], v[104:105], v[36:37] op_sel:[0,1] op_sel_hi:[1,0]
	v_pk_mul_f32 v[36:37], v[104:105], v[36:37]
	v_pk_mul_f32 v[98:99], v[106:107], v[38:39] op_sel:[0,1] op_sel_hi:[1,0]
	v_pk_mul_f32 v[38:39], v[106:107], v[38:39]
	v_pk_mul_f32 v[100:101], v[108:109], v[46:47] op_sel:[0,1] op_sel_hi:[1,0]
	v_pk_mul_f32 v[46:47], v[108:109], v[46:47]
	v_pk_mul_f32 v[102:103], v[110:111], v[40:41] op_sel:[0,1] op_sel_hi:[1,0]
	v_pk_mul_f32 v[40:41], v[110:111], v[40:41]
	v_sub_f32_e32 v33, v50, v51
	v_add_f32_e32 v48, v49, v48
	v_sub_f32_e32 v49, v52, v53
	v_add_f32_e32 v42, v43, v42
	v_sub_f32_e32 v43, v54, v55
	v_add_f32_e32 v34, v35, v34
	v_sub_f32_e32 v35, v58, v59
	v_add_f32_e32 v44, v45, v44
	v_sub_f32_e32 v45, v96, v97
	v_add_f32_e32 v36, v37, v36
	v_sub_f32_e32 v37, v98, v99
	v_add_f32_e32 v38, v39, v38
	v_sub_f32_e32 v39, v100, v101
	v_add_f32_e32 v46, v47, v46
	v_sub_f32_e32 v47, v102, v103
	v_add_f32_e32 v40, v41, v40
	v_cvt_pk_bf16_f32 v124, v33, v49
	v_cvt_pk_bf16_f32 v125, v43, v35
; __device__ __forceinline__ unsigned cvt_pk(float lo, float hi) { unsigned r; asm volatile("v_cvt_pk_bf16_f32 %0, %1, %2" : "=v"(r) : "v"(lo), "v"(hi)); return r; }
; __device__ __forceinline__ float bflo(unsigned w) { return __uint_as_float(w << 16); }
; __device__ __forceinline__ float bfhi(unsigned w) { return __uint_as_float(w & 0xffff0000u); }
; __device__ __forceinline__ void attn_body(const bf16_t* __restrict__ Qb, const bf16_t* __restrict__ Kh, const bf16_t* __restrict__ Vh, const bf16_t* __restrict__ Zb, ...
;     ...
;             for (int dd = 0; dd < 2; ++dd) { const int da = ax * 4 + dd, db = da + 2;
;                 const u32x4 wa = *reinterpret_cast<const u32x4*>(&qr[da]), wb = *reinterpret_cast<const u32x4*>(&qr[db]);
;                 float xa[8] = {bflo(wa.x), bfhi(wa.x), bflo(wa.y), bfhi(wa.y), bflo(wa.z), bfhi(wa.z), bflo(wa.w), bfhi(wa.w)};
;                 float xb[8] = {bflo(wb.x), bfhi(wb.x), bflo(wb.y), bfhi(wb.y), bflo(wb.z), bfhi(wb.z), bflo(wb.w), bfhi(wb.w)};
;                 const float* ga = qg_ + da * 16 + hi_ * 8; const float* gb = qg_ + db * 16 + hi_ * 8;
;                 const f32x4* tp = (const f32x4*)(rope_ + ((ax ? (tpos & 63) : (tpos >> 6)) * 32 + dd * 16 + hi_ * 8) * 2);
;                 const f32x4 t0 = tp[0], t1 = tp[1], t2 = tp[2], t3 = tp[3];
;                 const float csv[8] = {t0[0], t0[2], t1[0], t1[2], t2[0], t2[2], t3[0], t3[2]}, snv[8] = {t0[1], t0[3], t1[1], t1[3], t2[1], t2[3], t3[1], t3[3]};
; #pragma unroll
;                 for (int e = 0; e < 8; ++e) { const float x1 = xa[e] * rinv * ga[e], x2 = xb[e] * rinv * gb[e];
;                     xa[e] = x1 * csv[e] - x2 * snv[e]; xb[e] = x2 * csv[e] + x1 * snv[e]; }
;                 u32x4 oa, ob; oa.x = cvt_pk(xa[0], xa[1]); oa.y = cvt_pk(xa[2], xa[3]); oa.z = cvt_pk(xa[4], xa[5]); oa.w = cvt_pk(xa[6], xa[7]);
;                 ob.x = cvt_pk(xb[0], xb[1]); ob.y = cvt_pk(xb[2], xb[3]); ob.z = cvt_pk(xb[4], xb[5]); ob.w = cvt_pk(xb[6], xb[7]);
;                 qr[da] = *reinterpret_cast<bf16x8*>(&oa); qr[db] = *reinterpret_cast<bf16x8*>(&ob);
;                 __builtin_amdgcn_sched_barrier(0); }
	v_cvt_pk_bf16_f32 v126, v45, v37
	v_cvt_pk_bf16_f32 v127, v39, v47
	v_cvt_pk_bf16_f32 v120, v48, v42
	v_cvt_pk_bf16_f32 v121, v34, v44
	v_cvt_pk_bf16_f32 v122, v36, v38
	v_cvt_pk_bf16_f32 v123, v46, v40
	v_lshlrev_b32_e32 v33, 6, v164
	v_and_b32_e32 v33, 0xfc0, v33
	v_add_u32_e32 v50, v165, v33
	flat_load_dwordx4 v[34:37], v[68:69] offset:384
	flat_load_dwordx4 v[38:41], v[68:69] offset:256
	flat_load_dwordx4 v[42:45], v[68:69] offset:400
	flat_load_dwordx4 v[46:49], v[68:69] offset:272
	v_ashrrev_i32_e32 v51, 31, v50
	v_lshl_add_u64 v[54:55], v[50:51], 2, s[6:7]
	flat_load_dwordx4 v[50:53], v[54:55]
	flat_load_dwordx4 v[96:99], v[54:55] offset:16
	flat_load_dwordx4 v[100:103], v[54:55] offset:32
	flat_load_dwordx4 v[104:107], v[54:55] offset:48
	v_mov_b32_e32 v58, v82
	v_mov_b32_e32 v59, v60
	v_mov_b32_e32 v108, v84
	v_mov_b32_e32 v109, v62
	v_mov_b32_e32 v110, v86
	v_mov_b32_e32 v111, v64
	v_mov_b32_e32 v128, v88
	v_mov_b32_e32 v129, v66
	v_mov_b32_e32 v130, v90
	v_mov_b32_e32 v131, v70
	v_mov_b32_e32 v132, v80
	v_mov_b32_e32 v133, v72
	v_mov_b32_e32 v134, v78
	v_mov_b32_e32 v135, v74
	v_mov_b32_e32 v136, v56
	v_mov_b32_e32 v137, v76
	v_pk_mul_f32 v[58:59], v[32:33], v[58:59] op_sel_hi:[0,1]
	v_pk_mul_f32 v[108:109], v[32:33], v[108:109] op_sel_hi:[0,1]
	v_pk_mul_f32 v[110:111], v[32:33], v[110:111] op_sel_hi:[0,1]
	v_pk_mul_f32 v[128:129], v[32:33], v[128:129] op_sel_hi:[0,1]
	v_pk_mul_f32 v[130:131], v[32:33], v[130:131] op_sel_hi:[0,1]
	v_pk_mul_f32 v[132:133], v[32:33], v[132:133] op_sel_hi:[0,1]
	v_pk_mul_f32 v[134:135], v[32:33], v[134:135] op_sel_hi:[0,1]
	v_pk_mul_f32 v[136:137], v[32:33], v[136:137] op_sel_hi:[0,1]
	s_waitcnt vmcnt(0) lgkmcnt(0)
	v_mov_b32_e32 v138, v34
	v_mov_b32_e32 v139, v38
	v_mov_b32_e32 v38, v35
	v_mov_b32_e32 v34, v36
	v_mov_b32_e32 v35, v40
	v_mov_b32_e32 v40, v37
	v_mov_b32_e32 v36, v42
	v_mov_b32_e32 v37, v46
	v_mov_b32_e32 v46, v43
	v_mov_b32_e32 v42, v44
	v_mov_b32_e32 v43, v48
	v_mov_b32_e32 v48, v45
	v_pk_mul_f32 v[44:45], v[58:59], v[138:139]
	v_pk_mul_f32 v[38:39], v[108:109], v[38:39]
	v_pk_mul_f32 v[34:35], v[110:111], v[34:35]
	v_pk_mul_f32 v[40:41], v[128:129], v[40:41]
	v_pk_mul_f32 v[36:37], v[130:131], v[36:37]
	v_pk_mul_f32 v[46:47], v[132:133], v[46:47]
	v_pk_mul_f32 v[42:43], v[134:135], v[42:43]
	v_pk_mul_f32 v[48:49], v[136:137], v[48:49]
	v_pk_mul_f32 v[58:59], v[50:51], v[44:45] op_sel:[0,1] op_sel_hi:[1,0]
	v_pk_mul_f32 v[44:45], v[50:51], v[44:45]
	v_pk_mul_f32 v[50:51], v[52:53], v[38:39] op_sel:[0,1] op_sel_hi:[1,0]
	v_pk_mul_f32 v[38:39], v[52:53], v[38:39]
	v_pk_mul_f32 v[52:53], v[96:97], v[34:35] op_sel:[0,1] op_sel_hi:[1,0]
	v_pk_mul_f32 v[34:35], v[96:97], v[34:35]
	v_pk_mul_f32 v[96:97], v[98:99], v[40:41] op_sel:[0,1] op_sel_hi:[1,0]
	v_pk_mul_f32 v[40:41], v[98:99], v[40:41]
	v_pk_mul_f32 v[98:99], v[100:101], v[36:37] op_sel:[0,1] op_sel_hi:[1,0]
	v_pk_mul_f32 v[36:37], v[100:101], v[36:37]
	v_pk_mul_f32 v[100:101], v[102:103], v[46:47] op_sel:[0,1] op_sel_hi:[1,0]
	v_pk_mul_f32 v[46:47], v[102:103], v[46:47]
	v_pk_mul_f32 v[102:103], v[104:105], v[42:43] op_sel:[0,1] op_sel_hi:[1,0]
	v_pk_mul_f32 v[42:43], v[104:105], v[42:43]
	v_pk_mul_f32 v[104:105], v[106:107], v[48:49] op_sel:[0,1] op_sel_hi:[1,0]
	v_add_f32_e32 v44, v45, v44
	v_sub_f32_e32 v45, v50, v51
	v_add_f32_e32 v50, v35, v34
	v_pk_mul_f32 v[34:35], v[106:107], v[48:49]
	v_sub_f32_e32 v33, v58, v59
	v_add_f32_e32 v38, v39, v38
	v_sub_f32_e32 v39, v52, v53
	v_sub_f32_e32 v51, v96, v97
	v_add_f32_e32 v40, v41, v40
	v_sub_f32_e32 v41, v98, v99
	v_add_f32_e32 v36, v37, v36
	v_sub_f32_e32 v37, v100, v101
	v_add_f32_e32 v46, v47, v46
	v_sub_f32_e32 v47, v102, v103
	v_add_f32_e32 v42, v43, v42
	v_sub_f32_e32 v43, v104, v105
	v_add_f32_e32 v34, v35, v34
	v_cvt_pk_bf16_f32 v132, v33, v45
	v_cvt_pk_bf16_f32 v133, v39, v51
	v_cvt_pk_bf16_f32 v134, v41, v37
	v_cvt_pk_bf16_f32 v135, v47, v43
	v_cvt_pk_bf16_f32 v128, v44, v38
	v_cvt_pk_bf16_f32 v129, v50, v40
	v_cvt_pk_bf16_f32 v130, v36, v46
	v_cvt_pk_bf16_f32 v131, v42, v34
	flat_load_dwordx4 v[34:37], v[68:69] offset:448
	flat_load_dwordx4 v[38:41], v[68:69] offset:320
	flat_load_dwordx4 v[42:45], v[68:69] offset:464
	flat_load_dwordx4 v[46:49], v[68:69] offset:336
	flat_load_dwordx4 v[50:53], v[54:55] offset:128
	flat_load_dwordx4 v[96:99], v[54:55] offset:144
	flat_load_dwordx4 v[100:103], v[54:55] offset:160
	flat_load_dwordx4 v[104:107], v[54:55] offset:176
	v_mov_b32_e32 v60, v83
	v_mov_b32_e32 v62, v85
	v_mov_b32_e32 v64, v87
	v_mov_b32_e32 v66, v89
	v_mov_b32_e32 v70, v91
	v_mov_b32_e32 v72, v81
	v_mov_b32_e32 v74, v79
	v_mov_b32_e32 v76, v57
	v_pk_mul_f32 v[54:55], v[32:33], v[60:61] op_sel_hi:[0,1]
	v_pk_mul_f32 v[56:57], v[32:33], v[62:63] op_sel_hi:[0,1]
	v_pk_mul_f32 v[58:59], v[32:33], v[64:65] op_sel_hi:[0,1]
	v_pk_mul_f32 v[60:61], v[32:33], v[66:67] op_sel_hi:[0,1]
	v_pk_mul_f32 v[62:63], v[32:33], v[70:71] op_sel_hi:[0,1]
	v_pk_mul_f32 v[64:65], v[32:33], v[72:73] op_sel_hi:[0,1]
	v_pk_mul_f32 v[66:67], v[32:33], v[74:75] op_sel_hi:[0,1]
	v_pk_mul_f32 v[32:33], v[32:33], v[76:77] op_sel_hi:[0,1]
	s_waitcnt vmcnt(0) lgkmcnt(0)
; __device__ __forceinline__ unsigned cvt_pk(float lo, float hi) { unsigned r; asm volatile("v_cvt_pk_bf16_f32 %0, %1, %2" : "=v"(r) : "v"(lo), "v"(hi)); return r; }
; #define SWRITE(b, i) do { *(bf16x8*)((char*)V_lds + (b) * SHM_V + vst0) = sr_[i].vs0;          \
;     *(bf16x8*)((char*)V_lds + (b) * SHM_V + vst1) = sr_[i].vs1; int kc = sc * 2;               \
;     *(bf16x8*)((char*)K_lds + (b) * SHM_K + KSWZ(sr, kc)) = sr_[i].ks0;                       \
;     *(bf16x8*)((char*)K_lds + (b) * SHM_K + KSWZ(32 + sr, kc)) = sr_[i].ks1; } while (0)
; __device__ __forceinline__ void qkt(f32x16& p0, f32x16& p1, const bf16_t* Ks, const bf16x8* qr, int r32, int hi) {
;     p0 = f32x16{}; p1 = f32x16{};
;     for (int d0 = 0; d0 < 8; ++d0) { int cb = (d0 * 16 + hi * 8) * 2;
;         bf16x8 b0 = *reinterpret_cast<const bf16x8*>((const char*)Ks + KSWZ(r32, cb));
;         bf16x8 b1 = *reinterpret_cast<const bf16x8*>((const char*)Ks + KSWZ(32 + r32, cb));
;         p0 = __builtin_amdgcn_mfma_f32_32x32x16_bf16(b0, qr[d0], p0, 0, 0, 0);
;         p1 = __builtin_amdgcn_mfma_f32_32x32x16_bf16(b1, qr[d0], p1, 0, 0, 0); }
; }
; __device__ __forceinline__ void attn_body(const bf16_t* __restrict__ Qb, const bf16_t* __restrict__ Kh, const bf16_t* __restrict__ Vh, const bf16_t* __restrict__ Zb, ...
;     ...
;                 for (int e = 0; e < 8; ++e) { const float x1 = xa[e] * rinv * ga[e], x2 = xb[e] * rinv * gb[e];
;                     xa[e] = x1 * csv[e] - x2 * snv[e]; xb[e] = x2 * csv[e] + x1 * snv[e]; }
;                 u32x4 oa, ob; oa.x = cvt_pk(xa[0], xa[1]); oa.y = cvt_pk(xa[2], xa[3]); oa.z = cvt_pk(xa[4], xa[5]); oa.w = cvt_pk(xa[6], xa[7]);
;                 ob.x = cvt_pk(xb[0], xb[1]); ob.y = cvt_pk(xb[2], xb[3]); ob.z = cvt_pk(xb[4], xb[5]); ob.w = cvt_pk(xb[6], xb[7]);
;                 qr[da] = *reinterpret_cast<bf16x8*>(&oa); qr[db] = *reinterpret_cast<bf16x8*>(&ob);
;                 __builtin_amdgcn_sched_barrier(0); }
;     }
;     ...
;     f32x16 pA0, pA1, pB0, pB1; bf16x8 pa0, pa1, pa2, pa3; const int NT = seq / KVBLK;
;     constexpr int SE = 0, SO = 1;
;     asm volatile("s_waitcnt vmcnt(0)" ::: "memory"); SWRITE(0, SE); __syncthreads();
;     qkt(pA0, pA1, K_lds, qr, r32, hi); partialSM(pA0, pA1, negBC);
	v_mov_b32_e32 v68, v34
	v_mov_b32_e32 v69, v38
	v_mov_b32_e32 v38, v35
	v_mov_b32_e32 v34, v36
	v_mov_b32_e32 v35, v40
	v_mov_b32_e32 v40, v37
	v_mov_b32_e32 v36, v42
	v_mov_b32_e32 v37, v46
	v_mov_b32_e32 v46, v43
	v_mov_b32_e32 v42, v44
	v_mov_b32_e32 v43, v48
	v_mov_b32_e32 v48, v45
	v_pk_mul_f32 v[44:45], v[54:55], v[68:69]
	v_pk_mul_f32 v[38:39], v[56:57], v[38:39]
	v_pk_mul_f32 v[34:35], v[58:59], v[34:35]
	v_pk_mul_f32 v[40:41], v[60:61], v[40:41]
	v_pk_mul_f32 v[36:37], v[62:63], v[36:37]
	v_pk_mul_f32 v[46:47], v[64:65], v[46:47]
	v_pk_mul_f32 v[42:43], v[66:67], v[42:43]
	v_pk_mul_f32 v[32:33], v[32:33], v[48:49]
	v_pk_mul_f32 v[48:49], v[50:51], v[44:45] op_sel:[0,1] op_sel_hi:[1,0]
	v_pk_mul_f32 v[44:45], v[50:51], v[44:45]
	v_pk_mul_f32 v[50:51], v[52:53], v[38:39] op_sel:[0,1] op_sel_hi:[1,0]
	v_pk_mul_f32 v[38:39], v[52:53], v[38:39]
	v_pk_mul_f32 v[52:53], v[96:97], v[34:35] op_sel:[0,1] op_sel_hi:[1,0]
	v_pk_mul_f32 v[34:35], v[96:97], v[34:35]
	v_pk_mul_f32 v[54:55], v[98:99], v[40:41] op_sel:[0,1] op_sel_hi:[1,0]
	v_pk_mul_f32 v[40:41], v[98:99], v[40:41]
	v_pk_mul_f32 v[56:57], v[100:101], v[36:37] op_sel:[0,1] op_sel_hi:[1,0]
	v_pk_mul_f32 v[36:37], v[100:101], v[36:37]
	v_pk_mul_f32 v[58:59], v[102:103], v[46:47] op_sel:[0,1] op_sel_hi:[1,0]
	v_pk_mul_f32 v[46:47], v[102:103], v[46:47]
	v_pk_mul_f32 v[60:61], v[104:105], v[42:43] op_sel:[0,1] op_sel_hi:[1,0]
	v_pk_mul_f32 v[42:43], v[104:105], v[42:43]
	v_pk_mul_f32 v[62:63], v[106:107], v[32:33] op_sel:[0,1] op_sel_hi:[1,0]
	v_pk_mul_f32 v[32:33], v[106:107], v[32:33]
	v_sub_f32_e32 v48, v48, v49
	v_add_f32_e32 v44, v45, v44
	v_sub_f32_e32 v45, v50, v51
	v_add_f32_e32 v38, v39, v38
	v_sub_f32_e32 v39, v52, v53
	v_add_f32_e32 v34, v35, v34
	v_sub_f32_e32 v35, v54, v55
	v_add_f32_e32 v40, v41, v40
	v_sub_f32_e32 v41, v56, v57
	v_add_f32_e32 v36, v37, v36
	v_sub_f32_e32 v37, v58, v59
	v_add_f32_e32 v46, v47, v46
	v_sub_f32_e32 v47, v60, v61
	v_add_f32_e32 v42, v43, v42
	v_sub_f32_e32 v43, v62, v63
	v_add_f32_e32 v32, v33, v32
	v_cvt_pk_bf16_f32 v140, v48, v45
	v_cvt_pk_bf16_f32 v141, v39, v35
	v_cvt_pk_bf16_f32 v142, v41, v37
	v_cvt_pk_bf16_f32 v143, v47, v43
	v_cvt_pk_bf16_f32 v136, v44, v38
	v_cvt_pk_bf16_f32 v137, v34, v40
	v_cvt_pk_bf16_f32 v138, v36, v46
	v_cvt_pk_bf16_f32 v139, v42, v32
	v_or3_b32 v32, v92, v93, v95
	v_add_u32_e32 v207, 0, v32
	s_waitcnt vmcnt(0)
	ds_write_b128 v207, v[8:11]
	v_lshlrev_b32_e32 v8, 8, v186
	v_and_b32_e32 v9, 0xf0, v200
	v_bitop3_b32 v8, v188, v8, v9 bitop3:0xde
	v_add_u32_e32 v208, 0, v94
	v_add_u32_e32 v209, 0, v8
	ds_write_b128 v208, v[12:15]
	ds_write_b128 v209, v[4:7] offset:32768
	v_lshlrev_b32_e32 v4, 8, v189
	v_bitop3_b32 v4, v188, v4, v9 bitop3:0xde
	v_add_u32_e32 v210, 0, v4
	ds_write_b128 v210, v[0:3] offset:32768
	v_lshlrev_b32_e32 v0, 4, v200
	v_lshlrev_b32_e32 v40, 8, v201
	v_and_b32_e32 v41, 0xf0, v0
	v_bitop3_b32 v0, v184, v40, v41 bitop3:0xde
	v_add_u32_e32 v211, 0, v0
	s_waitcnt lgkmcnt(0)
	s_barrier
	ds_read_b128 v[0:3], v211 offset:32768
	ds_read_b128 v[32:35], v211 offset:40960
	s_waitcnt lgkmcnt(1)
	v_mfma_f32_32x32x16_bf16 v[0:15], v[0:3], v[116:119], 0
	v_cmp_ne_u32_e64 s[6:7], 1, v197
	s_andn2_b64 vcc, exec, s[4:5]
	s_waitcnt lgkmcnt(0)
	v_mfma_f32_32x32x16_bf16 v[64:79], v[32:35], v[116:119], 0
	v_or_b32_e32 v32, 32, v184
	v_bitop3_b32 v32, v32, v40, v41 bitop3:0xde
	v_add_u32_e32 v212, 0, v32
	ds_read_b128 v[32:35], v212 offset:32768
	ds_read_b128 v[36:39], v212 offset:40960
	s_waitcnt lgkmcnt(1)
	v_mfma_f32_32x32x16_bf16 v[0:15], v[32:35], v[124:127], v[0:15]
	v_or_b32_e32 v32, 64, v184
	v_bitop3_b32 v32, v32, v40, v41 bitop3:0xde
	v_add_u32_e32 v213, 0, v32
	s_waitcnt lgkmcnt(0)
	v_mfma_f32_32x32x16_bf16 v[64:79], v[36:39], v[124:127], v[64:79]
	ds_read_b128 v[32:35], v213 offset:32768
	ds_read_b128 v[36:39], v213 offset:40960
	s_waitcnt lgkmcnt(1)
	v_mfma_f32_32x32x16_bf16 v[0:15], v[32:35], v[112:115], v[0:15]
	v_or_b32_e32 v32, 0x60, v184
	v_bitop3_b32 v32, v32, v40, v41 bitop3:0xde
	v_add_u32_e32 v214, 0, v32
	s_waitcnt lgkmcnt(0)
	v_mfma_f32_32x32x16_bf16 v[64:79], v[36:39], v[112:115], v[64:79]
	ds_read_b128 v[32:35], v214 offset:32768
	ds_read_b128 v[36:39], v214 offset:40960
	s_waitcnt lgkmcnt(1)
	v_mfma_f32_32x32x16_bf16 v[0:15], v[32:35], v[120:123], v[0:15]
	v_or_b32_e32 v32, 0x80, v184
	v_bitop3_b32 v32, v32, v40, v41 bitop3:0xde
	v_add_u32_e32 v215, 0, v32
	s_waitcnt lgkmcnt(0)
	v_mfma_f32_32x32x16_bf16 v[64:79], v[36:39], v[120:123], v[64:79]
	ds_read_b128 v[32:35], v215 offset:32768
	ds_read_b128 v[36:39], v215 offset:40960
	s_waitcnt lgkmcnt(1)
	v_mfma_f32_32x32x16_bf16 v[0:15], v[32:35], v[132:135], v[0:15]
	v_or_b32_e32 v32, 0xa0, v184
	v_bitop3_b32 v32, v32, v40, v41 bitop3:0xde
	v_add_u32_e32 v216, 0, v32
	s_waitcnt lgkmcnt(0)
	v_mfma_f32_32x32x16_bf16 v[64:79], v[36:39], v[132:135], v[64:79]
	ds_read_b128 v[32:35], v216 offset:32768
	ds_read_b128 v[36:39], v216 offset:40960
	s_waitcnt lgkmcnt(1)
	v_mfma_f32_32x32x16_bf16 v[0:15], v[32:35], v[140:143], v[0:15]
	v_or_b32_e32 v32, 0xc0, v184
	v_bitop3_b32 v32, v32, v40, v41 bitop3:0xde
	v_add_u32_e32 v217, 0, v32
	s_waitcnt lgkmcnt(0)
	v_mfma_f32_32x32x16_bf16 v[64:79], v[36:39], v[140:143], v[64:79]
	ds_read_b128 v[32:35], v217 offset:32768
	ds_read_b128 v[36:39], v217 offset:40960
	s_waitcnt lgkmcnt(1)
	v_mfma_f32_32x32x16_bf16 v[0:15], v[32:35], v[128:131], v[0:15]
	v_or_b32_e32 v32, 0xe0, v184
	v_bitop3_b32 v32, v32, v40, v41 bitop3:0xde
	v_add_u32_e32 v218, 0, v32
	s_waitcnt lgkmcnt(0)
	v_mfma_f32_32x32x16_bf16 v[64:79], v[36:39], v[128:131], v[64:79]
	ds_read_b128 v[32:35], v218 offset:32768
	ds_read_b128 v[36:39], v218 offset:40960
	s_waitcnt lgkmcnt(1)
	v_mfma_f32_32x32x16_bf16 v[0:15], v[32:35], v[136:139], v[0:15]
	s_waitcnt lgkmcnt(0)
	v_mfma_f32_32x32x16_bf16 v[64:79], v[36:39], v[136:139], v[64:79]
	s_cbranch_vccnz .LBB0_487
	v_mov_b32_e32 v181, v180
	s_nop 7
	v_pk_add_f32 v[14:15], v[180:181], v[14:15]
	v_pk_add_f32 v[12:13], v[180:181], v[12:13]
	v_pk_add_f32 v[10:11], v[180:181], v[10:11]
	v_pk_add_f32 v[8:9], v[180:181], v[8:9]
	v_pk_add_f32 v[6:7], v[180:181], v[6:7]
	v_pk_add_f32 v[4:5], v[180:181], v[4:5]
	v_pk_add_f32 v[2:3], v[180:181], v[2:3]
	v_pk_add_f32 v[0:1], v[182:183], v[0:1]
	v_pk_add_f32 v[78:79], v[180:181], v[78:79]
	v_pk_add_f32 v[76:77], v[180:181], v[76:77]
	v_pk_add_f32 v[74:75], v[180:181], v[74:75]
	v_pk_add_f32 v[72:73], v[180:181], v[72:73]
	v_pk_add_f32 v[70:71], v[180:181], v[70:71]
	v_pk_add_f32 v[68:69], v[180:181], v[68:69]
	v_pk_add_f32 v[66:67], v[180:181], v[66:67]
	v_pk_add_f32 v[64:65], v[182:183], v[64:65]
